# gMLP tile 0: tril(W) fragment LDS reads run 11 ahead of the 20 MFMAs (k-step-major order) instead of read-wait-MFMA chains
# baseline (speedup 1.0000x reference)
; #define LAS __attribute__((address_space(3)))
; __device__ __forceinline__ bf16x8 pack8(f32x4 lo, f32x4 hi) { v4u w; w.x = pk2(lo[0], lo[1]); w.y = pk2(lo[2], lo[3]); w.z = pk2(hi[0], hi[1]); w.w = pk2(hi[2], hi[3]); return __builtin_bit_cast(bf16x8, w); }
; __device__ __forceinline__ void gmlp_compute(GmlpRegs& R, const Args& a, const Ctx& C, int c, int hd) {
;     ...
;     const int lane = C.lane, fr = lane & 15, q = lane >> 4, w = C.wave, tid = C.tid;
;     const size_t T0 = (size_t)c * 128; const int chs = hd * 128 + 16 * w + 4 * q;
;     ...
;     const float lg = R.lg, lb = R.lb;
;     bf16x8 af[4];
; #pragma unroll
;     for (int ks = 0; ks < 4; ++ks) { f32x4 lo, hi;
; #pragma unroll
;         for (int e = 0; e < 8; ++e) { const int sl = 32 * ks + 8 * q + e;
;             const float v = __uint_as_float((unsigned)*(const LAS unsigned short*)(VL + sl * 260 + (16 * w + fr) * 2) << 16);
;             const float x = (v - ST[2 * sl]) * ST[2 * sl + 1] * lg + lb; if (e < 4) lo[e] = x; else hi[e - 4] = x; }
;         af[ks] = pack8(lo, hi); }
.LBB0_971:
	s_or_b64 exec, exec, s[76:77]
	v_or_b32_e32 v144, s2, v149
	v_lshrrev_b32_e32 v145, 4, v162
	v_lshl_add_u32 v165, v144, 1, 0
	s_movk_i32 s74, 0x820
	v_mad_u32_u24 v62, v145, s74, v165
	s_waitcnt lgkmcnt(0)
	s_barrier
	v_lshlrev_b32_e32 v63, 6, v145
	s_add_i32 s2, 0, 0x10a00
	v_add_u32_e32 v183, s2, v63
	v_lshlrev_b32_e32 v153, 3, v145
	v_or_b32_e32 v64, 2, v153
	s_waitcnt vmcnt(28)
	v_mov_b32_e32 v99, v98
	v_lshlrev_b32_e32 v52, 3, v64
	v_add_u32_e32 v168, s2, v52
	v_mov_b32_e32 v101, v100
	v_mul_u32_u24_e32 v167, 0x104, v64
	s_mov_b32 s74, 0x18000
	s_mov_b32 s75, 0x20000
	s_mov_b32 s76, 0x28000
	s_mov_b32 s77, 0x30000
	v_or_b32_e32 v52, 32, v63
	v_add_u32_e32 v163, s2, v52
	s_mov_b32 s78, 0x38000
	v_mul_u32_u24_e32 v184, 0x820, v145
	v_mul_u32_u24_e32 v200, 0x110, v149
	s_nop 0
	v_or_b32_e32 v52, 48, v63
	v_add_u32_e32 v166, s2, v52
	s_nop 0
	v_or_b32_e32 v54, 0x100, v63
	v_add_u32_e32 v185, s2, v54
	s_nop 0
	v_or_b32_e32 v54, 0x110, v63
	v_add_u32_e32 v186, s2, v54
	v_or_b32_e32 v65, 0x220, v63
	v_add_u32_e32 v192, s2, v65
	s_nop 0
	v_or_b32_e32 v54, 0x120, v63
	v_add_u32_e32 v188, s2, v54
	v_mov_b32_e32 v54, 0x2288
	v_mad_u32_u24 v54, v64, s33, v54
	v_add_u32_e32 v187, v165, v54
	s_nop 0
	v_or_b32_e32 v54, 0x130, v63
	v_add_u32_e32 v189, s2, v54
	v_or_b32_e32 v58, 0x200, v63
	v_add_u32_e32 v190, s2, v58
	v_or_b32_e32 v60, 0x210, v63
	v_add_u32_e32 v191, s2, v60
	v_or_b32_e32 v65, 0x230, v63
	v_add_u32_e32 v194, s2, v65
	v_mov_b32_e32 v65, 0x4510
	v_mad_u32_u24 v64, v64, s33, v65
	v_add_u32_e32 v193, v165, v64
	s_mov_b32 s33, 0x10000
	s_nop 0
	v_or_b32_e32 v64, 0x300, v63
	v_add_u32_e32 v195, s2, v64
	s_nop 0
	v_or_b32_e32 v64, 0x310, v63
	v_add_u32_e32 v196, s2, v64
	s_nop 0
	v_or_b32_e32 v64, 0x320, v63
	v_add_u32_e32 v197, s2, v64
	v_or_b32_e32 v63, 0x330, v63
	v_add_u32_e32 v198, s2, v63
	s_mov_b32 s2, 0x8000
	v_and_b32_e32 v66, 48, v0
	v_add_u32_e32 v199, 0, v66
	v_mad_u32_u24 v112, v149, s1, v199
	v_lshlrev_b32_e32 v82, 6, v145
	v_add_u32_e32 v82, 0x10a00, v82
	ds_read_u16 v66, v62 offset:34816
	ds_read_u16 v67, v62 offset:35076
	ds_read_u16 v68, v62 offset:35336
	ds_read_u16 v69, v62 offset:35596
	ds_read_u16 v70, v62 offset:35856
	ds_read_u16 v71, v62 offset:36116
	ds_read_u16 v72, v62 offset:36376
	ds_read_u16 v73, v62 offset:36636
	ds_read_b128 v[204:207], v82
	ds_read_b128 v[208:211], v82 offset:16
	ds_read_b128 v[212:215], v82 offset:32
	ds_read_b128 v[216:219], v82 offset:48
	ds_read_u16 v74, v62 offset:43136
	ds_read_u16 v75, v62 offset:43396
	ds_read_u16 v76, v62 offset:43656
	ds_read_u16 v77, v62 offset:43916
	ds_read_u16 v78, v62 offset:44176
	ds_read_u16 v79, v62 offset:44436
	ds_read_u16 v80, v62 offset:44696
	ds_read_u16 v81, v62 offset:44956
	ds_read_b128 v[220:223], v82 offset:256
	ds_read_b128 v[224:227], v82 offset:272
	ds_read_b128 v[228:231], v82 offset:288
	ds_read_b128 v[232:235], v82 offset:304
	s_waitcnt lgkmcnt(12)
	v_lshlrev_b32_e32 v66, 16, v66
	v_lshlrev_b32_e32 v67, 16, v67
	v_lshlrev_b32_e32 v68, 16, v68
	v_lshlrev_b32_e32 v69, 16, v69
	v_lshlrev_b32_e32 v70, 16, v70
	v_lshlrev_b32_e32 v71, 16, v71
	v_lshlrev_b32_e32 v72, 16, v72
	v_lshlrev_b32_e32 v73, 16, v73
	v_sub_f32_e32 v66, v66, v204
	v_sub_f32_e32 v67, v67, v206
	v_sub_f32_e32 v68, v68, v208
	v_sub_f32_e32 v69, v69, v210
	v_sub_f32_e32 v70, v70, v212
	v_sub_f32_e32 v71, v71, v214
	v_sub_f32_e32 v72, v72, v216
	v_sub_f32_e32 v73, v73, v218
	v_mul_f32_e32 v66, v205, v66
	v_mul_f32_e32 v67, v207, v67
	v_mul_f32_e32 v68, v209, v68
	v_mul_f32_e32 v69, v211, v69
	v_mul_f32_e32 v70, v213, v70
	v_mul_f32_e32 v71, v215, v71
	v_mul_f32_e32 v72, v217, v72
	v_mul_f32_e32 v73, v219, v73
	v_fma_f32 v66, v98, v66, v100
	v_fma_f32 v67, v98, v67, v100
	v_fma_f32 v68, v98, v68, v100
	v_fma_f32 v69, v98, v69, v100
	v_fma_f32 v70, v98, v70, v100
	v_fma_f32 v71, v98, v71, v100
	v_fma_f32 v72, v98, v72, v100
	v_fma_f32 v73, v98, v73, v100
	v_cvt_pk_bf16_f32 v50, v66, v67
	v_cvt_pk_bf16_f32 v51, v68, v69
	v_cvt_pk_bf16_f32 v52, v70, v71
	v_cvt_pk_bf16_f32 v53, v72, v73
	ds_read_u16 v66, v62 offset:51456
	ds_read_u16 v67, v62 offset:51716
	ds_read_u16 v68, v62 offset:51976
	ds_read_u16 v69, v62 offset:52236
	ds_read_u16 v70, v62 offset:52496
	ds_read_u16 v71, v62 offset:52756
	ds_read_u16 v72, v62 offset:53016
	ds_read_u16 v73, v62 offset:53276
	ds_read_b128 v[204:207], v82 offset:512
	ds_read_b128 v[208:211], v82 offset:528
	ds_read_b128 v[212:215], v82 offset:544
	ds_read_b128 v[216:219], v82 offset:560
	s_waitcnt lgkmcnt(12)
	v_lshlrev_b32_e32 v74, 16, v74
	v_lshlrev_b32_e32 v75, 16, v75
	v_lshlrev_b32_e32 v76, 16, v76
	v_lshlrev_b32_e32 v77, 16, v77
	v_lshlrev_b32_e32 v78, 16, v78
	v_lshlrev_b32_e32 v79, 16, v79
	v_lshlrev_b32_e32 v80, 16, v80
	v_lshlrev_b32_e32 v81, 16, v81
	v_sub_f32_e32 v74, v74, v220
	v_sub_f32_e32 v75, v75, v222
	v_sub_f32_e32 v76, v76, v224
	v_sub_f32_e32 v77, v77, v226
	v_sub_f32_e32 v78, v78, v228
	v_sub_f32_e32 v79, v79, v230
	v_sub_f32_e32 v80, v80, v232
	v_sub_f32_e32 v81, v81, v234
	v_mul_f32_e32 v74, v221, v74
	v_mul_f32_e32 v75, v223, v75
	v_mul_f32_e32 v76, v225, v76
	v_mul_f32_e32 v77, v227, v77
	v_mul_f32_e32 v78, v229, v78
	v_mul_f32_e32 v79, v231, v79
	v_mul_f32_e32 v80, v233, v80
	v_mul_f32_e32 v81, v235, v81
	v_fma_f32 v74, v98, v74, v100
	v_fma_f32 v75, v98, v75, v100
	v_fma_f32 v76, v98, v76, v100
	v_fma_f32 v77, v98, v77, v100
	v_fma_f32 v78, v98, v78, v100
	v_fma_f32 v79, v98, v79, v100
	v_fma_f32 v80, v98, v80, v100
	v_fma_f32 v81, v98, v81, v100
	v_cvt_pk_bf16_f32 v54, v74, v75
	v_cvt_pk_bf16_f32 v55, v76, v77
	v_cvt_pk_bf16_f32 v56, v78, v79
	v_cvt_pk_bf16_f32 v57, v80, v81
	ds_read_u16 v74, v62 offset:59776
	ds_read_u16 v75, v62 offset:60036
	ds_read_u16 v76, v62 offset:60296
	ds_read_u16 v77, v62 offset:60556
	ds_read_u16 v78, v62 offset:60816
	ds_read_u16 v79, v62 offset:61076
	ds_read_u16 v80, v62 offset:61336
	ds_read_u16 v81, v62 offset:61596
	ds_read_b128 v[220:223], v82 offset:768
	ds_read_b128 v[224:227], v82 offset:784
	ds_read_b128 v[228:231], v82 offset:800
	ds_read_b128 v[232:235], v82 offset:816
	s_waitcnt lgkmcnt(12)
; #define LAS __attribute__((address_space(3)))
; #define MFMA16(A, B, Cc) __builtin_amdgcn_mfma_f32_16x16x32_bf16((A), (B), (Cc), 0, 0, 0)
; #define PIN(x) asm volatile("" : "+v"(x))
; __device__ __forceinline__ float bf_lo(unsigned w) { return __uint_as_float(w << 16); }
; __device__ __forceinline__ unsigned pk4f8(float a, float b, float c, float d) { int p = __builtin_amdgcn_cvt_pk_fp8_f32(sat8(a), sat8(b), 0, false); p = __builtin_amdgcn_cvt_pk_fp8_f32(sat8(c), sat8(d), p, true); return (unsigned)p; }
; __device__ __forceinline__ float bf_hi(unsigned w) { return __uint_as_float(w & 0xffff0000u); }
; __device__ __forceinline__ bf16x8 pack8(f32x4 lo, f32x4 hi) { v4u w; w.x = pk2(lo[0], lo[1]); w.y = pk2(lo[2], lo[3]); w.z = pk2(hi[0], hi[1]); w.w = pk2(hi[2], hi[3]); return __builtin_bit_cast(bf16x8, w); }
; __device__ __forceinline__ void gmlp_compute(GmlpRegs& R, const Args& a, const Ctx& C, int c, int hd) {
;     ...
;     for (int ks = 0; ks < 4; ++ks) { f32x4 lo, hi;
; #pragma unroll
;         for (int e = 0; e < 8; ++e) { const int sl = 32 * ks + 8 * q + e;
;             const float v = __uint_as_float((unsigned)*(const LAS unsigned short*)(VL + sl * 260 + (16 * w + fr) * 2) << 16);
;             const float x = (v - ST[2 * sl]) * ST[2 * sl + 1] * lg + lb; if (e < 4) lo[e] = x; else hi[e - 4] = x; }
;         af[ks] = pack8(lo, hi); }
;     f32x4 acc[8];
; #pragma unroll
;     for (int nt = 0; nt < 8; ++nt) { acc[nt] = (f32x4){0.f, 0.f, 0.f, 0.f};
; #pragma unroll
;         for (int ks = 0; ks <= nt / 2; ++ks) acc[nt] = MFMA16(af[ks], *(const LAS bf16x8*)(WL + (16 * nt + fr) * 272 + (32 * ks + 8 * q) * 2), acc[nt]); }
; #pragma unroll
;     for (int nt = 0; nt < 8; ++nt) PIN(R.uq[nt]);
; #pragma unroll
;     for (int nt = 0; nt < 8; ++nt) { const size_t row = T0 + 16 * nt + fr; const float bs = R.bsv[nt];
;         const float o0 = bf_lo(R.uq[nt].x) * (acc[nt][0] + bs), o1 = bf_hi(R.uq[nt].x) * (acc[nt][1] + bs);
;         const float o2 = bf_lo(R.uq[nt].y) * (acc[nt][2] + bs), o3 = bf_hi(R.uq[nt].y) * (acc[nt][3] + bs);
;         *(unsigned*)((unsigned char*)Y + row * DM + chs) = pk4f8(o0, o1, o2, o3); }
	v_lshlrev_b32_e32 v66, 16, v66
	v_lshlrev_b32_e32 v67, 16, v67
	v_lshlrev_b32_e32 v68, 16, v68
	v_lshlrev_b32_e32 v69, 16, v69
	v_lshlrev_b32_e32 v70, 16, v70
	v_lshlrev_b32_e32 v71, 16, v71
	v_lshlrev_b32_e32 v72, 16, v72
	v_lshlrev_b32_e32 v73, 16, v73
	v_sub_f32_e32 v66, v66, v204
	v_sub_f32_e32 v67, v67, v206
	v_sub_f32_e32 v68, v68, v208
	v_sub_f32_e32 v69, v69, v210
	v_sub_f32_e32 v70, v70, v212
	v_sub_f32_e32 v71, v71, v214
	v_sub_f32_e32 v72, v72, v216
	v_sub_f32_e32 v73, v73, v218
	v_mul_f32_e32 v66, v205, v66
	v_mul_f32_e32 v67, v207, v67
	v_mul_f32_e32 v68, v209, v68
	v_mul_f32_e32 v69, v211, v69
	v_mul_f32_e32 v70, v213, v70
	v_mul_f32_e32 v71, v215, v71
	v_mul_f32_e32 v72, v217, v72
	v_mul_f32_e32 v73, v219, v73
	v_fma_f32 v66, v98, v66, v100
	v_fma_f32 v67, v98, v67, v100
	v_fma_f32 v68, v98, v68, v100
	v_fma_f32 v69, v98, v69, v100
	v_fma_f32 v70, v98, v70, v100
	v_fma_f32 v71, v98, v71, v100
	v_fma_f32 v72, v98, v72, v100
	v_fma_f32 v73, v98, v73, v100
	v_cvt_pk_bf16_f32 v58, v66, v67
	v_cvt_pk_bf16_f32 v59, v68, v69
	v_cvt_pk_bf16_f32 v60, v70, v71
	v_cvt_pk_bf16_f32 v61, v72, v73
	s_waitcnt lgkmcnt(0)
	v_lshlrev_b32_e32 v74, 16, v74
	v_lshlrev_b32_e32 v75, 16, v75
	v_lshlrev_b32_e32 v76, 16, v76
	v_lshlrev_b32_e32 v77, 16, v77
	v_lshlrev_b32_e32 v78, 16, v78
	v_lshlrev_b32_e32 v79, 16, v79
	v_lshlrev_b32_e32 v80, 16, v80
	v_lshlrev_b32_e32 v81, 16, v81
	v_sub_f32_e32 v74, v74, v220
	v_sub_f32_e32 v75, v75, v222
	v_sub_f32_e32 v76, v76, v224
	v_sub_f32_e32 v77, v77, v226
	v_sub_f32_e32 v78, v78, v228
	v_sub_f32_e32 v79, v79, v230
	v_sub_f32_e32 v80, v80, v232
	v_sub_f32_e32 v81, v81, v234
	v_mul_f32_e32 v74, v221, v74
	v_mul_f32_e32 v75, v223, v75
	v_mul_f32_e32 v76, v225, v76
	v_mul_f32_e32 v77, v227, v77
	v_mul_f32_e32 v78, v229, v78
	v_mul_f32_e32 v79, v231, v79
	v_mul_f32_e32 v80, v233, v80
	v_mul_f32_e32 v81, v235, v81
	v_fma_f32 v74, v98, v74, v100
	v_fma_f32 v75, v98, v75, v100
	v_fma_f32 v76, v98, v76, v100
	v_fma_f32 v77, v98, v77, v100
	v_fma_f32 v78, v98, v78, v100
	v_fma_f32 v79, v98, v79, v100
	v_fma_f32 v80, v98, v80, v100
	v_fma_f32 v81, v98, v81, v100
	v_cvt_pk_bf16_f32 v62, v74, v75
	v_cvt_pk_bf16_f32 v63, v76, v77
	v_cvt_pk_bf16_f32 v64, v78, v79
	v_cvt_pk_bf16_f32 v65, v80, v81
	ds_read_b128 v[202:205], v112
	ds_read_b128 v[206:209], v112 offset:4352
	ds_read_b128 v[210:213], v112 offset:8704
	ds_read_b128 v[214:217], v112 offset:13056
	ds_read_b128 v[218:221], v112 offset:17408
	ds_read_b128 v[222:225], v112 offset:21760
	ds_read_b128 v[226:229], v112 offset:26112
	ds_read_b128 v[230:233], v112 offset:30464
	ds_read_b128 v[234:237], v112 offset:8768
	ds_read_b128 v[238:241], v112 offset:13120
	ds_read_b128 v[242:245], v112 offset:17472
	s_waitcnt lgkmcnt(10)
	v_mfma_f32_16x16x32_bf16 v[78:81], v[50:53], v[202:205], 0
	ds_read_b128 v[202:205], v112 offset:21824
	s_waitcnt lgkmcnt(10)
	v_mfma_f32_16x16x32_bf16 v[66:69], v[50:53], v[206:209], 0
	ds_read_b128 v[206:209], v112 offset:26176
	s_waitcnt lgkmcnt(10)
	v_mfma_f32_16x16x32_bf16 v[70:73], v[50:53], v[210:213], 0
	ds_read_b128 v[210:213], v112 offset:30528
	s_waitcnt lgkmcnt(10)
	v_mfma_f32_16x16x32_bf16 v[74:77], v[50:53], v[214:217], 0
	ds_read_b128 v[214:217], v112 offset:17536
	s_waitcnt lgkmcnt(10)
	v_mfma_f32_16x16x32_bf16 v[82:85], v[50:53], v[218:221], 0
	ds_read_b128 v[218:221], v112 offset:21888
	s_waitcnt lgkmcnt(10)
	v_mfma_f32_16x16x32_bf16 v[86:89], v[50:53], v[222:225], 0
	ds_read_b128 v[222:225], v112 offset:26240
	s_waitcnt lgkmcnt(10)
	v_mfma_f32_16x16x32_bf16 v[90:93], v[50:53], v[226:229], 0
	ds_read_b128 v[226:229], v112 offset:30592
	s_waitcnt lgkmcnt(10)
	v_mfma_f32_16x16x32_bf16 v[50:53], v[50:53], v[230:233], 0
	ds_read_b128 v[230:233], v112 offset:26304
	s_waitcnt lgkmcnt(10)
	v_mfma_f32_16x16x32_bf16 v[70:73], v[54:57], v[234:237], v[70:73]
	ds_read_b128 v[234:237], v112 offset:30656
	s_waitcnt lgkmcnt(10)
	v_mfma_f32_16x16x32_bf16 v[74:77], v[54:57], v[238:241], v[74:77]
	s_waitcnt lgkmcnt(9)
	v_mfma_f32_16x16x32_bf16 v[82:85], v[54:57], v[242:245], v[82:85]
	s_waitcnt lgkmcnt(8)
	v_mfma_f32_16x16x32_bf16 v[86:89], v[54:57], v[202:205], v[86:89]
	s_waitcnt lgkmcnt(7)
	v_mfma_f32_16x16x32_bf16 v[90:93], v[54:57], v[206:209], v[90:93]
	s_waitcnt lgkmcnt(6)
	v_mfma_f32_16x16x32_bf16 v[50:53], v[54:57], v[210:213], v[50:53]
	s_waitcnt lgkmcnt(5)
	v_mfma_f32_16x16x32_bf16 v[82:85], v[58:61], v[214:217], v[82:85]
	s_waitcnt lgkmcnt(4)
	v_mfma_f32_16x16x32_bf16 v[86:89], v[58:61], v[218:221], v[86:89]
	s_waitcnt lgkmcnt(3)
	v_mfma_f32_16x16x32_bf16 v[90:93], v[58:61], v[222:225], v[90:93]
	s_waitcnt lgkmcnt(2)
	v_mfma_f32_16x16x32_bf16 v[50:53], v[58:61], v[226:229], v[50:53]
	s_waitcnt lgkmcnt(1)
	v_mfma_f32_16x16x32_bf16 v[90:93], v[62:65], v[230:233], v[90:93]
	s_waitcnt lgkmcnt(0)
	v_mfma_f32_16x16x32_bf16 v[50:53], v[62:65], v[234:237], v[50:53]
	s_mov_b32 s1, 0xc3e00000
	s_waitcnt vmcnt(27)
	v_lshlrev_b32_e32 v112, 2, v145
	v_lshlrev_b32_e32 v54, 16, v140
	s_waitcnt vmcnt(19)
	v_add_f32_e32 v55, v161, v78
	v_mul_f32_e32 v54, v55, v54
	v_and_b32_e32 v55, 0xffff0000, v140
	v_add_f32_e32 v56, v161, v79
	v_or_b32_e32 v128, s0, v112
	v_mul_f32_e32 v55, v56, v55
	v_lshlrev_b32_e32 v56, 16, v141
	v_add_f32_e32 v57, v161, v80
	v_lshl_add_u64 v[142:143], s[70:71], 0, v[128:129]
	v_mul_f32_e32 v56, v57, v56
	v_and_b32_e32 v57, 0xffff0000, v141
	v_add_f32_e32 v58, v161, v81
	v_mov_b32_e32 v128, 0x43e00000
	v_mul_f32_e32 v57, v58, v57
	v_med3_f32 v54, v54, s1, v128
	v_med3_f32 v55, v55, s1, v128
	v_mov_b32_e32 v58, v129
	v_cvt_pk_fp8_f32 v58, v54, v55
	v_med3_f32 v54, v56, s1, v128
	v_med3_f32 v55, v57, s1, v128
	v_cvt_pk_fp8_f32 v58, v54, v55 op_sel:[0,0,1]
	v_lshlrev_b64 v[54:55], 11, v[136:137]
	v_lshl_add_u64 v[54:55], v[142:143], 0, v[54:55]
	v_lshlrev_b32_e32 v56, 16, v138
	s_waitcnt vmcnt(18)
; __device__ __forceinline__ float bf_lo(unsigned w) { return __uint_as_float(w << 16); }
; __device__ __forceinline__ unsigned pk4f8(float a, float b, float c, float d) { int p = __builtin_amdgcn_cvt_pk_fp8_f32(sat8(a), sat8(b), 0, false); p = __builtin_amdgcn_cvt_pk_fp8_f32(sat8(c), sat8(d), p, true); return (unsigned)p; }
; __device__ __forceinline__ float bf_hi(unsigned w) { return __uint_as_float(w & 0xffff0000u); }
; __device__ __forceinline__ void s5_xs_load(v4u (&xv)[8], const Args& a, const Ctx& C, int b, int g) {
;     const bf16* XBg = (const bf16*)(a.ws + WS_XB) + ((size_t)g * MP + (size_t)b * SEQ) * 16;
; #pragma unroll
;     for (int i = 0; i < 8; ++i) xv[i] = __builtin_nontemporal_load((const v4u*)(XBg + (size_t)(C.tid + 512 * i) * 8));
; }
; __device__ __forceinline__ void gmlp_compute(GmlpRegs& R, const Args& a, const Ctx& C, int c, int hd) {
;     ...
;     for (int nt = 0; nt < 8; ++nt) { const size_t row = T0 + 16 * nt + fr; const float bs = R.bsv[nt];
;         const float o0 = bf_lo(R.uq[nt].x) * (acc[nt][0] + bs), o1 = bf_hi(R.uq[nt].x) * (acc[nt][1] + bs);
;         const float o2 = bf_lo(R.uq[nt].y) * (acc[nt][2] + bs), o3 = bf_hi(R.uq[nt].y) * (acc[nt][3] + bs);
;         *(unsigned*)((unsigned char*)Y + row * DM + chs) = pk4f8(o0, o1, o2, o3); }
	v_add_f32_e32 v57, v160, v66
	global_store_dword v[54:55], v58, off
	v_mul_f32_e32 v56, v57, v56
	v_and_b32_e32 v57, 0xffff0000, v138
	v_add_f32_e32 v58, v160, v67
	v_mul_f32_e32 v57, v58, v57
	v_lshlrev_b32_e32 v58, 16, v139
	v_add_f32_e32 v59, v160, v68
	v_mul_f32_e32 v58, v59, v58
	v_and_b32_e32 v59, 0xffff0000, v139
	v_add_f32_e32 v60, v160, v69
	v_mul_f32_e32 v59, v60, v59
	v_med3_f32 v56, v56, s1, v128
	v_med3_f32 v57, v57, s1, v128
	v_mov_b32_e32 v60, v129
	v_cvt_pk_fp8_f32 v60, v56, v57
	v_med3_f32 v56, v58, s1, v128
	v_med3_f32 v57, v59, s1, v128
	s_waitcnt vmcnt(18)
	v_add_f32_e32 v58, v159, v71
	v_cvt_pk_fp8_f32 v60, v56, v57 op_sel:[0,0,1]
	v_add_co_u32_e64 v56, s[70:71], s2, v54
	v_add_f32_e32 v59, v159, v72
	s_nop 0
	v_addc_co_u32_e64 v57, s[70:71], 0, v55, s[70:71]
	global_store_dword v[56:57], v60, off
	v_lshlrev_b32_e32 v56, 16, v134
	v_add_f32_e32 v57, v159, v70
	v_mul_f32_e32 v56, v57, v56
	v_and_b32_e32 v57, 0xffff0000, v134
	v_mul_f32_e32 v57, v58, v57
	v_lshlrev_b32_e32 v58, 16, v135
	v_mul_f32_e32 v58, v59, v58
	v_and_b32_e32 v59, 0xffff0000, v135
	v_add_f32_e32 v60, v159, v73
	v_mul_f32_e32 v59, v60, v59
	v_med3_f32 v56, v56, s1, v128
	v_med3_f32 v57, v57, s1, v128
	v_mov_b32_e32 v60, v129
	v_cvt_pk_fp8_f32 v60, v56, v57
	v_med3_f32 v56, v58, s1, v128
	v_med3_f32 v57, v59, s1, v128
	s_waitcnt vmcnt(18)
	v_add_f32_e32 v58, v156, v75
	v_cvt_pk_fp8_f32 v60, v56, v57 op_sel:[0,0,1]
	v_add_co_u32_e64 v56, s[70:71], s33, v54
	v_add_f32_e32 v59, v156, v76
	s_nop 0
	v_addc_co_u32_e64 v57, s[70:71], 0, v55, s[70:71]
	global_store_dword v[56:57], v60, off
	v_lshlrev_b32_e32 v56, 16, v132
	v_add_f32_e32 v57, v156, v74
	v_mul_f32_e32 v56, v57, v56
	v_and_b32_e32 v57, 0xffff0000, v132
	v_mul_f32_e32 v57, v58, v57
	v_lshlrev_b32_e32 v58, 16, v133
	v_mul_f32_e32 v58, v59, v58
	v_and_b32_e32 v59, 0xffff0000, v133
	v_add_f32_e32 v60, v156, v77
	v_mul_f32_e32 v59, v60, v59
	v_med3_f32 v56, v56, s1, v128
	v_med3_f32 v57, v57, s1, v128
	v_mov_b32_e32 v60, v129
	v_cvt_pk_fp8_f32 v60, v56, v57
	v_med3_f32 v56, v58, s1, v128
	v_med3_f32 v57, v59, s1, v128
	s_waitcnt vmcnt(18)
	v_add_f32_e32 v58, v154, v83
	v_cvt_pk_fp8_f32 v60, v56, v57 op_sel:[0,0,1]
	v_add_co_u32_e64 v56, s[70:71], s74, v54
	v_add_f32_e32 v59, v154, v84
	s_nop 0
	v_addc_co_u32_e64 v57, s[70:71], 0, v55, s[70:71]
	global_store_dword v[56:57], v60, off
	v_lshlrev_b32_e32 v56, 16, v130
	v_add_f32_e32 v57, v154, v82
	v_mul_f32_e32 v56, v57, v56
	v_and_b32_e32 v57, 0xffff0000, v130
	v_mul_f32_e32 v57, v58, v57
	v_lshlrev_b32_e32 v58, 16, v131
	v_mul_f32_e32 v58, v59, v58
	v_and_b32_e32 v59, 0xffff0000, v131
	v_add_f32_e32 v60, v154, v85
	v_mul_f32_e32 v59, v60, v59
	v_med3_f32 v56, v56, s1, v128
	v_med3_f32 v57, v57, s1, v128
	v_mov_b32_e32 v60, v129
	v_cvt_pk_fp8_f32 v60, v56, v57
	v_med3_f32 v56, v58, s1, v128
	v_med3_f32 v57, v59, s1, v128
	s_waitcnt vmcnt(18)
	v_add_f32_e32 v58, v152, v87
	v_cvt_pk_fp8_f32 v60, v56, v57 op_sel:[0,0,1]
	v_add_co_u32_e64 v56, s[70:71], s75, v54
	v_add_f32_e32 v59, v152, v88
	s_nop 0
	v_addc_co_u32_e64 v57, s[70:71], 0, v55, s[70:71]
	global_store_dword v[56:57], v60, off
	v_lshlrev_b32_e32 v56, 16, v126
	v_add_f32_e32 v57, v152, v86
	v_mul_f32_e32 v56, v57, v56
	v_and_b32_e32 v57, 0xffff0000, v126
	v_mul_f32_e32 v57, v58, v57
	v_lshlrev_b32_e32 v58, 16, v127
	v_mul_f32_e32 v58, v59, v58
	v_and_b32_e32 v59, 0xffff0000, v127
	v_add_f32_e32 v60, v152, v89
	v_mul_f32_e32 v59, v60, v59
	v_med3_f32 v56, v56, s1, v128
	v_med3_f32 v57, v57, s1, v128
	v_mov_b32_e32 v60, v129
	v_cvt_pk_fp8_f32 v60, v56, v57
	v_med3_f32 v56, v58, s1, v128
	v_med3_f32 v57, v59, s1, v128
	s_waitcnt vmcnt(18)
	v_add_f32_e32 v58, v151, v91
	v_cvt_pk_fp8_f32 v60, v56, v57 op_sel:[0,0,1]
	v_add_co_u32_e64 v56, s[70:71], s76, v54
	v_add_f32_e32 v59, v151, v92
	s_nop 0
	v_addc_co_u32_e64 v57, s[70:71], 0, v55, s[70:71]
	global_store_dword v[56:57], v60, off
	v_lshlrev_b32_e32 v56, 16, v124
	v_add_f32_e32 v57, v151, v90
	v_mul_f32_e32 v56, v57, v56
	v_and_b32_e32 v57, 0xffff0000, v124
	v_mul_f32_e32 v57, v58, v57
	v_lshlrev_b32_e32 v58, 16, v125
	v_mul_f32_e32 v58, v59, v58
	v_and_b32_e32 v59, 0xffff0000, v125
	v_add_f32_e32 v60, v151, v93
	v_mul_f32_e32 v59, v60, v59
	v_med3_f32 v56, v56, s1, v128
	v_med3_f32 v57, v57, s1, v128
	v_mov_b32_e32 v60, v129
	v_cvt_pk_fp8_f32 v60, v56, v57
	v_med3_f32 v56, v58, s1, v128
	v_med3_f32 v57, v59, s1, v128
	s_waitcnt vmcnt(18)
	v_add_f32_e32 v50, v150, v50
	v_cvt_pk_fp8_f32 v60, v56, v57 op_sel:[0,0,1]
	v_add_co_u32_e64 v56, s[70:71], s77, v54
	v_add_f32_e32 v51, v150, v51
	s_nop 0
	v_addc_co_u32_e64 v57, s[70:71], 0, v55, s[70:71]
	global_store_dword v[56:57], v60, off
	v_lshlrev_b32_e32 v56, 16, v122
	v_mul_f32_e32 v50, v50, v56
	v_and_b32_e32 v56, 0xffff0000, v122
	v_mul_f32_e32 v51, v51, v56
	v_med3_f32 v50, v50, s1, v128
	v_med3_f32 v51, v51, s1, v128
	v_lshlrev_b32_e32 v56, 16, v123
	v_add_f32_e32 v52, v150, v52
	v_cvt_pk_fp8_f32 v129, v50, v51
	v_mul_f32_e32 v52, v52, v56
	v_and_b32_e32 v56, 0xffff0000, v123
	v_add_f32_e32 v53, v150, v53
	v_mul_f32_e32 v53, v53, v56
	v_med3_f32 v50, v52, s1, v128
	v_med3_f32 v51, v53, s1, v128
	v_cvt_pk_fp8_f32 v129, v50, v51 op_sel:[0,0,1]
	v_add_co_u32_e64 v50, s[70:71], s78, v54
	v_readlane_b32 s0, v249, 0
	s_nop 0
	v_addc_co_u32_e64 v51, s[70:71], 0, v55, s[70:71]
	s_ashr_i32 s70, s0, 6
	s_ashr_i32 s71, s70, 31
	s_and_b32 s0, s0, 63
	s_lshl_b64 s[80:81], s[70:71], 16
	s_add_u32 s79, s94, s80
	s_addc_u32 s80, s95, s81
	s_mul_i32 s81, s0, 0x42000
	s_add_u32 s79, s79, s81
	s_addc_u32 s81, s80, 0
	s_add_u32 s80, s79, 0xc200000
	global_store_dword v[50:51], v129, off
	s_addc_u32 s81, s81, 0
	v_lshlrev_b32_e32 v87, 4, v146
	v_lshlrev_b32_e32 v86, 4, v95
	v_lshlrev_b32_e32 v85, 4, v120
	v_lshlrev_b32_e32 v84, 4, v157
	v_lshlrev_b32_e32 v83, 4, v158
	v_lshlrev_b32_e32 v82, 4, v155
	global_load_dwordx4 v[74:77], v94, s[80:81] nt
	global_load_dwordx4 v[78:81], v87, s[80:81] nt
	global_load_dwordx4 v[70:73], v148, s[80:81] nt
	global_load_dwordx4 v[66:69], v86, s[80:81] nt
	global_load_dwordx4 v[58:61], v85, s[80:81] nt
	global_load_dwordx4 v[62:65], v84, s[80:81] nt
	global_load_dwordx4 v[50:53], v83, s[80:81] nt
	global_load_dwordx4 v[54:57], v82, s[80:81] nt
	s_nop 0
	v_cndmask_b32_e64 v26, v26, 0, s[68:69]
	v_cndmask_b32_e64 v27, 0, v27, s[4:5]
	v_cndmask_b32_e64 v28, v28, 0, s[6:7]
	v_cndmask_b32_e64 v29, v29, 0, s[8:9]
	v_cvt_pk_bf16_f32 v26, v26, v27
	v_cvt_pk_bf16_f32 v27, v28, v29
	v_add_u32_e32 v28, v164, v169
	s_waitcnt vmcnt(27)
	s_waitcnt vmcnt(26)
	s_waitcnt vmcnt(25)
	s_waitcnt vmcnt(24)
	s_barrier
; #define LAS __attribute__((address_space(3)))
; __device__ __forceinline__ unsigned pk2(float lo, float hi) { return pg8::cvt_pk_bf16(lo, hi); }
; __device__ __forceinline__ void gmlp_compute(GmlpRegs& R, const Args& a, const Ctx& C, int c, int hd) {
;     ...
; #pragma unroll
;     for (int i = 0; i < 8; ++i) { const int idx = tid + 512 * i, tr = idx >> 5, c4 = (idx & 31) * 4; f32x4 x = R.wv[i];
; #pragma unroll
;         for (int j = 0; j < 4; ++j) x[j] = (c4 + j <= tr) ? x[j] : 0.f;
;         *(LAS v2u*)(WL + tr * 272 + c4 * 2) = (v2u){pk2(x[0], x[1]), pk2(x[2], x[3])}; }
; #pragma unroll
;     for (int i = 0; i < 4; ++i) { const int idx = tid + 512 * i; LAS unsigned* d = (LAS unsigned*)(VL + (idx >> 4) * 260 + (idx & 15) * 16); d[0] = R.vv[i].x; d[1] = R.vv[i].y; d[2] = R.vv[i].z; d[3] = R.vv[i].w; }
;     if (tid < 128) { const float mu = R.s1 * (1.0f / DA), var = R.s2 * (1.0f / DA) - mu * mu; ST[2 * tid] = mu; ST[2 * tid + 1] = __builtin_amdgcn_rsqf(var + EPS); }
	ds_write_b64 v28, v[26:27]
	v_cndmask_b32_e64 v26, v30, 0, s[10:11]
	v_cndmask_b32_e64 v27, 0, v31, s[14:15]
	v_cndmask_b32_e64 v28, v32, 0, s[16:17]
	v_cndmask_b32_e64 v29, v33, 0, s[18:19]
	v_cndmask_b32_e64 v18, v18, 0, s[20:21]
	v_cndmask_b32_e64 v19, 0, v19, s[22:23]
	v_cndmask_b32_e64 v20, v20, 0, s[24:25]
	v_cndmask_b32_e64 v21, v21, 0, s[26:27]
	v_cvt_pk_bf16_f32 v26, v26, v27
	v_cvt_pk_bf16_f32 v27, v28, v29
	v_add_u32_e32 v28, v164, v170
	v_cvt_pk_bf16_f32 v18, v18, v19
	v_cvt_pk_bf16_f32 v19, v20, v21
	v_add_u32_e32 v20, v164, v171
	ds_write_b64 v28, v[26:27]
	ds_write_b64 v20, v[18:19]
	v_cndmask_b32_e64 v18, v22, 0, s[72:73]
	v_cndmask_b32_e64 v19, 0, v23, s[28:29]
	v_cndmask_b32_e64 v20, v24, 0, s[30:31]
	v_cndmask_b32_e64 v21, v25, 0, s[34:35]
	v_cndmask_b32_e64 v10, v10, 0, s[36:37]
	v_cndmask_b32_e64 v11, 0, v11, s[38:39]
	v_cndmask_b32_e64 v12, v12, 0, s[40:41]
	v_cndmask_b32_e64 v13, v13, 0, s[42:43]
	v_cvt_pk_bf16_f32 v18, v18, v19
	v_cvt_pk_bf16_f32 v19, v20, v21
	v_add_u32_e32 v20, v164, v172
	v_cvt_pk_bf16_f32 v10, v10, v11
	v_cvt_pk_bf16_f32 v11, v12, v13
	v_add_u32_e32 v12, v164, v173
	ds_write_b64 v20, v[18:19]
	ds_write_b64 v12, v[10:11]
	v_cndmask_b32_e64 v10, v14, 0, s[44:45]
	v_cndmask_b32_e64 v11, 0, v15, s[46:47]
	v_cndmask_b32_e64 v12, v16, 0, s[48:49]
	v_cndmask_b32_e64 v13, v17, 0, s[50:51]
	v_cndmask_b32_e64 v6, v6, 0, s[52:53]
	v_cndmask_b32_e64 v7, 0, v7, s[54:55]
	v_cndmask_b32_e64 v8, v8, 0, s[56:57]
	v_cndmask_b32_e64 v9, v9, 0, s[58:59]
	v_cndmask_b32_e64 v2, v2, 0, s[60:61]
	v_cndmask_b32_e64 v3, 0, v3, s[62:63]
	v_cndmask_b32_e64 v4, v4, 0, s[64:65]
	v_cndmask_b32_e64 v5, v5, 0, s[66:67]
	v_cvt_pk_bf16_f32 v10, v10, v11
	v_cvt_pk_bf16_f32 v11, v12, v13
	v_add_u32_e32 v12, v164, v174
	v_cvt_pk_bf16_f32 v6, v6, v7
	v_cvt_pk_bf16_f32 v7, v8, v9
	v_add_u32_e32 v8, v164, v176
	v_cvt_pk_bf16_f32 v2, v2, v3
	v_cvt_pk_bf16_f32 v3, v4, v5
	v_add_u32_e32 v4, v164, v178
	ds_write_b64 v12, v[10:11]
	ds_write_b64 v8, v[6:7]
	ds_write_b64 v4, v[2:3]
	v_add_u32_e32 v2, v175, v179
	v_add_u32_e32 v3, 0x8800, v2
	v_add_u32_e32 v2, 0x8808, v2
	ds_write2_b32 v2, v40, v41 offset1:1
	v_add_u32_e32 v2, v175, v180
	ds_write2_b32 v3, v38, v39 offset1:1
	v_add_u32_e32 v3, 0x8800, v2
	v_add_u32_e32 v2, 0x8808, v2
	ds_write2_b32 v2, v36, v37 offset1:1
	v_add_u32_e32 v2, v175, v181
	ds_write2_b32 v3, v34, v35 offset1:1
	v_add_u32_e32 v3, 0x8800, v2
	v_add_u32_e32 v2, 0x8808, v2
	ds_write2_b32 v2, v48, v49 offset1:1
	v_add_u32_e32 v2, v175, v182
	ds_write2_b32 v3, v46, v47 offset1:1
	v_add_u32_e32 v3, 0x8800, v2
	v_add_u32_e32 v2, 0x8808, v2
	ds_write2_b32 v3, v42, v43 offset1:1
	ds_write2_b32 v2, v44, v45 offset1:1
	s_and_saveexec_b64 s[4:5], vcc
	s_cbranch_execz .LBB0_973
	s_waitcnt vmcnt(24)
	v_mul_f32_e32 v113, 0x3a800000, v252
	v_mul_f32_e32 v121, 0x3a800000, v253
	v_fma_f32 v2, -v121, v121, v113
	v_add_f32_e32 v2, 0x358637bd, v2
	v_rsq_f32_e32 v3, v2
	v_add_u32_e32 v4, 0x10a00, v177
	v_mov_b32_e32 v2, v121
	ds_write_b64 v4, v[2:3]
